# v023 plus software-pipelined K-fragment LDS reads (5 buffers in flight) in both differential-attention QK blocks
# baseline (speedup 1.0000x reference)
; #define LAS __attribute__((address_space(3)))
; #define KSWZ(row, colB) (KPERM(row) * ROWB + ((colB) ^ (((row) & 7) << 4)))
; template <int DQK, bool ROPEQ, bool ALIBI> ...
;     ...
;             for (int d0 = 0; d0 < ND; ++d0) { const int cb = d0 * 32 + hi * 16;
;                 const bf16x8 b0 = *(const LAS bf16x8*)(Kl + b * KBYTES + KSWZ(r32, cb));
;                 const bf16x8 b1 = *(const LAS bf16x8*)(Kl + b * KBYTES + KSWZ(32 + r32, cb));
;                 p0 = __builtin_amdgcn_mfma_f32_32x32x16_bf16(b0, qr[d0], p0, 0, 0, 0);
;                 p1 = __builtin_amdgcn_mfma_f32_32x32x16_bf16(b1, qr[d0], p1, 0, 0, 0); }
;     ...
;             if constexpr (ALIBI) {
;                 float qk0 = (float)(qpos - j * 64 - 4 * hi); asm volatile("" : "+v"(qk0));
;                 if (j < qchunk) {
;                     base = -slope2 * qk0;
; #pragma unroll
;                     for (int r = 0; r < 16; ++r) { const float cr = (float)((r & 3) + 8 * (r >> 2)); p0[r] = fmaf(slope2, cr, p0[r]); p1[r] = fmaf(slope2, cr + 32.f, p1[r]); }
;                 } else {
; #pragma unroll
;                     for (int r = 0; r < 16; ++r) { const float cr = (float)((r & 3) + 8 * (r >> 2));
;                         p0[r] = fmaf(-slope2, fabsf(qk0 - cr), p0[r]); p1[r] = fmaf(-slope2, fabsf(qk0 - (cr + 32.f)), p1[r]); }
.LBB0_1189:
	v_lshl_add_u32 v74, s14, 13, v224
	v_add_u32_e32 v75, v74, v155
	v_add_u32_e32 v76, v74, v214
	v_add_u32_e32 v77, v74, v215
	v_add_u32_e32 v78, v74, v216
	ds_read_b128 v[66:69], v75 offset:49152
	ds_read_b128 v[70:73], v75 offset:53248
	ds_read_b128 v[240:243], v76 offset:49152
	ds_read_b128 v[246:249], v76 offset:53248
	ds_read_b128 v[250:253], v77 offset:49152
	v_cvt_f32_i32_e32 v204, v141
	s_mov_b64 vcc, -1
	s_cmp_lt_i32 s2, s15
	s_setprio 1
	s_waitcnt lgkmcnt(4)
	v_mfma_f32_32x32x16_bf16 v[98:113], v[66:69], v[114:117], 0
	ds_read_b128 v[66:69], v77 offset:53248
	s_waitcnt lgkmcnt(4)
	v_mfma_f32_32x32x16_bf16 v[82:97], v[70:73], v[114:117], 0
	ds_read_b128 v[70:73], v78 offset:49152
	s_waitcnt lgkmcnt(4)
	v_mfma_f32_32x32x16_bf16 v[98:113], v[240:243], v[118:121], v[98:113]
	ds_read_b128 v[240:243], v78 offset:53248
	s_waitcnt lgkmcnt(4)
	v_mfma_f32_32x32x16_bf16 v[82:97], v[246:249], v[118:121], v[82:97]
	s_waitcnt lgkmcnt(3)
	v_mfma_f32_32x32x16_bf16 v[98:113], v[250:253], v[122:125], v[98:113]
	s_waitcnt lgkmcnt(2)
	v_mfma_f32_32x32x16_bf16 v[82:97], v[66:69], v[122:125], v[82:97]
	s_waitcnt lgkmcnt(1)
	v_mfma_f32_32x32x16_bf16 v[98:113], v[70:73], v[126:129], v[98:113]
	s_waitcnt lgkmcnt(0)
	v_mfma_f32_32x32x16_bf16 v[82:97], v[240:243], v[126:129], v[82:97]
	s_setprio 0
	s_cbranch_scc1 .LBB0_1191
	v_add_f32_e32 v81, -1.0, v204
	v_pk_add_f32 v[66:67], v[204:205], s[16:17] op_sel_hi:[0,1]
	v_pk_add_f32 v[68:69], v[204:205], s[18:19] op_sel_hi:[0,1]
	v_pk_add_f32 v[70:71], v[204:205], s[22:23] op_sel_hi:[0,1]
	v_pk_add_f32 v[72:73], v[204:205], s[40:41] op_sel_hi:[0,1]
	v_pk_add_f32 v[74:75], v[204:205], s[42:43] op_sel_hi:[0,1]
	v_pk_add_f32 v[76:77], v[204:205], s[44:45] op_sel_hi:[0,1]
	v_pk_add_f32 v[78:79], v[204:205], s[46:47] op_sel_hi:[0,1]
	v_and_b32_e32 v67, 0x7fffffff, v67
	v_and_b32_e32 v66, 0x7fffffff, v66
	v_and_b32_e32 v69, 0x7fffffff, v69
	v_and_b32_e32 v68, 0x7fffffff, v68
	v_and_b32_e32 v71, 0x7fffffff, v71
	v_and_b32_e32 v70, 0x7fffffff, v70
	v_and_b32_e32 v73, 0x7fffffff, v73
	v_and_b32_e32 v72, 0x7fffffff, v72
	v_and_b32_e32 v75, 0x7fffffff, v75
	v_and_b32_e32 v74, 0x7fffffff, v74
	v_and_b32_e32 v77, 0x7fffffff, v77
	v_and_b32_e32 v76, 0x7fffffff, v76
	v_and_b32_e32 v79, 0x7fffffff, v79
	v_and_b32_e32 v78, 0x7fffffff, v78
	v_and_b32_e32 v80, 0x7fffffff, v204
	v_and_b32_e32 v81, 0x7fffffff, v81
	v_mov_b32_e32 v165, v164
	v_pk_fma_f32 v[190:191], v[164:165], v[78:79], v[112:113]
	v_pk_fma_f32 v[192:193], v[164:165], v[76:77], v[110:111]
	v_pk_fma_f32 v[194:195], v[164:165], v[74:75], v[108:109]
	v_pk_fma_f32 v[196:197], v[164:165], v[72:73], v[106:107]
	v_pk_fma_f32 v[198:199], v[164:165], v[70:71], v[104:105]
	v_pk_fma_f32 v[200:201], v[164:165], v[68:69], v[102:103]
	v_pk_fma_f32 v[202:203], v[164:165], v[66:67], v[100:101]
	v_pk_fma_f32 v[206:207], v[168:169], v[80:81], v[98:99]
	v_pk_add_f32 v[66:67], v[204:205], s[48:49] op_sel_hi:[0,1]
	v_pk_add_f32 v[68:69], v[204:205], s[50:51] op_sel_hi:[0,1]
	v_pk_add_f32 v[70:71], v[204:205], s[52:53] op_sel_hi:[0,1]
	v_pk_add_f32 v[72:73], v[204:205], s[54:55] op_sel_hi:[0,1]
	v_pk_add_f32 v[74:75], v[204:205], s[56:57] op_sel_hi:[0,1]
	v_pk_add_f32 v[76:77], v[204:205], s[58:59] op_sel_hi:[0,1]
	v_pk_add_f32 v[78:79], v[204:205], s[60:61] op_sel_hi:[0,1]
	v_pk_add_f32 v[80:81], v[204:205], s[62:63] op_sel_hi:[0,1]
	v_and_b32_e32 v233, 0x7fffffff, v81
	v_and_b32_e32 v232, 0x7fffffff, v80
	v_and_b32_e32 v235, 0x7fffffff, v79
	v_and_b32_e32 v234, 0x7fffffff, v78
	v_and_b32_e32 v237, 0x7fffffff, v77
	v_and_b32_e32 v236, 0x7fffffff, v76
	v_and_b32_e32 v239, 0x7fffffff, v75
	v_and_b32_e32 v238, 0x7fffffff, v74
	v_and_b32_e32 v73, 0x7fffffff, v73
	v_and_b32_e32 v72, 0x7fffffff, v72
	v_and_b32_e32 v71, 0x7fffffff, v71
	v_and_b32_e32 v70, 0x7fffffff, v70
	v_and_b32_e32 v69, 0x7fffffff, v69
	v_and_b32_e32 v68, 0x7fffffff, v68
	v_and_b32_e32 v67, 0x7fffffff, v67
	v_and_b32_e32 v66, 0x7fffffff, v66
	v_pk_fma_f32 v[80:81], v[164:165], v[66:67], v[96:97]
	v_pk_fma_f32 v[78:79], v[164:165], v[68:69], v[94:95]
	v_pk_fma_f32 v[76:77], v[164:165], v[70:71], v[92:93]
	v_pk_fma_f32 v[74:75], v[164:165], v[72:73], v[90:91]
	v_pk_fma_f32 v[72:73], v[164:165], v[238:239], v[88:89]
	v_pk_fma_f32 v[70:71], v[164:165], v[236:237], v[86:87]
	v_pk_fma_f32 v[68:69], v[164:165], v[234:235], v[84:85]
	v_pk_fma_f32 v[66:67], v[168:169], v[232:233], v[82:83]
	s_mov_b64 vcc, 0

; #define LAS __attribute__((address_space(3)))
; #define KSWZ(row, colB) (KPERM(row) * ROWB + ((colB) ^ (((row) & 7) << 4)))
; template <int DQK, bool ROPEQ, bool ALIBI> ...
;     ...
;             for (int d0 = 0; d0 < ND; ++d0) { const int cb = d0 * 32 + hi * 16;
;                 const bf16x8 b0 = *(const LAS bf16x8*)(Kl + b * KBYTES + KSWZ(r32, cb));
;                 const bf16x8 b1 = *(const LAS bf16x8*)(Kl + b * KBYTES + KSWZ(32 + r32, cb));
;                 p0 = __builtin_amdgcn_mfma_f32_32x32x16_bf16(b0, qr[d0], p0, 0, 0, 0);
;                 p1 = __builtin_amdgcn_mfma_f32_32x32x16_bf16(b1, qr[d0], p1, 0, 0, 0); }
;     ...
;             if constexpr (ALIBI) {
;                 float qk0 = (float)(qpos - j * 64 - 4 * hi); asm volatile("" : "+v"(qk0));
;                 if (j < qchunk) {
;                     base = -slope2 * qk0;
; #pragma unroll
;                     for (int r = 0; r < 16; ++r) { const float cr = (float)((r & 3) + 8 * (r >> 2)); p0[r] = fmaf(slope2, cr, p0[r]); p1[r] = fmaf(slope2, cr + 32.f, p1[r]); }
;                 } else {
; #pragma unroll
;                     for (int r = 0; r < 16; ++r) { const float cr = (float)((r & 3) + 8 * (r >> 2));
;                         p0[r] = fmaf(-slope2, fabsf(qk0 - cr), p0[r]); p1[r] = fmaf(-slope2, fabsf(qk0 - (cr + 32.f)), p1[r]); }
.LBB0_1210:
	v_lshl_add_u32 v74, s15, 13, v224
	v_add_u32_e32 v75, v74, v155
	v_add_u32_e32 v76, v74, v214
	v_add_u32_e32 v77, v74, v215
	v_add_u32_e32 v78, v74, v216
	ds_read_b128 v[66:69], v75 offset:49152
	ds_read_b128 v[70:73], v75 offset:53248
	ds_read_b128 v[240:243], v76 offset:49152
	ds_read_b128 v[246:249], v76 offset:53248
	ds_read_b128 v[250:253], v77 offset:49152
	v_cvt_f32_i32_e32 v188, v133
	s_mov_b64 vcc, -1
	s_cmp_lt_i32 s2, s14
	s_setprio 1
	s_waitcnt lgkmcnt(4)
	v_mfma_f32_32x32x16_bf16 v[98:113], v[66:69], v[114:117], 0
	ds_read_b128 v[66:69], v77 offset:53248
	s_waitcnt lgkmcnt(4)
	v_mfma_f32_32x32x16_bf16 v[82:97], v[70:73], v[114:117], 0
	ds_read_b128 v[70:73], v78 offset:49152
	s_waitcnt lgkmcnt(4)
	v_mfma_f32_32x32x16_bf16 v[98:113], v[240:243], v[118:121], v[98:113]
	ds_read_b128 v[240:243], v78 offset:53248
	s_waitcnt lgkmcnt(4)
	v_mfma_f32_32x32x16_bf16 v[82:97], v[246:249], v[118:121], v[82:97]
	s_waitcnt lgkmcnt(3)
	v_mfma_f32_32x32x16_bf16 v[98:113], v[250:253], v[122:125], v[98:113]
	s_waitcnt lgkmcnt(2)
	v_mfma_f32_32x32x16_bf16 v[82:97], v[66:69], v[122:125], v[82:97]
	s_waitcnt lgkmcnt(1)
	v_mfma_f32_32x32x16_bf16 v[98:113], v[70:73], v[126:129], v[98:113]
	s_waitcnt lgkmcnt(0)
	v_mfma_f32_32x32x16_bf16 v[82:97], v[240:243], v[126:129], v[82:97]
	s_setprio 0
	s_cbranch_scc1 .LBB0_1212
	v_add_f32_e32 v81, -1.0, v188
	v_pk_add_f32 v[66:67], v[188:189], s[16:17] op_sel_hi:[0,1]
	v_pk_add_f32 v[68:69], v[188:189], s[18:19] op_sel_hi:[0,1]
	v_pk_add_f32 v[70:71], v[188:189], s[22:23] op_sel_hi:[0,1]
	v_pk_add_f32 v[72:73], v[188:189], s[40:41] op_sel_hi:[0,1]
	v_pk_add_f32 v[74:75], v[188:189], s[42:43] op_sel_hi:[0,1]
	v_pk_add_f32 v[76:77], v[188:189], s[44:45] op_sel_hi:[0,1]
	v_pk_add_f32 v[78:79], v[188:189], s[46:47] op_sel_hi:[0,1]
	v_and_b32_e32 v67, 0x7fffffff, v67
	v_and_b32_e32 v66, 0x7fffffff, v66
	v_and_b32_e32 v69, 0x7fffffff, v69
	v_and_b32_e32 v68, 0x7fffffff, v68
	v_and_b32_e32 v71, 0x7fffffff, v71
	v_and_b32_e32 v70, 0x7fffffff, v70
	v_and_b32_e32 v73, 0x7fffffff, v73
	v_and_b32_e32 v72, 0x7fffffff, v72
	v_and_b32_e32 v75, 0x7fffffff, v75
	v_and_b32_e32 v74, 0x7fffffff, v74
	v_and_b32_e32 v77, 0x7fffffff, v77
	v_and_b32_e32 v76, 0x7fffffff, v76
	v_and_b32_e32 v79, 0x7fffffff, v79
	v_and_b32_e32 v78, 0x7fffffff, v78
	v_and_b32_e32 v80, 0x7fffffff, v188
	v_and_b32_e32 v81, 0x7fffffff, v81
	v_mov_b32_e32 v165, v164
	v_pk_fma_f32 v[174:175], v[164:165], v[78:79], v[112:113]
	v_pk_fma_f32 v[176:177], v[164:165], v[76:77], v[110:111]
	v_pk_fma_f32 v[178:179], v[164:165], v[74:75], v[108:109]
	v_pk_fma_f32 v[180:181], v[164:165], v[72:73], v[106:107]
	v_pk_fma_f32 v[182:183], v[164:165], v[70:71], v[104:105]
	v_pk_fma_f32 v[184:185], v[164:165], v[68:69], v[102:103]
	v_pk_fma_f32 v[186:187], v[164:165], v[66:67], v[100:101]
	v_pk_fma_f32 v[190:191], v[168:169], v[80:81], v[98:99]
	v_pk_add_f32 v[66:67], v[188:189], s[48:49] op_sel_hi:[0,1]
	v_pk_add_f32 v[68:69], v[188:189], s[50:51] op_sel_hi:[0,1]
	v_pk_add_f32 v[70:71], v[188:189], s[52:53] op_sel_hi:[0,1]
	v_pk_add_f32 v[72:73], v[188:189], s[54:55] op_sel_hi:[0,1]
	v_pk_add_f32 v[74:75], v[188:189], s[56:57] op_sel_hi:[0,1]
	v_pk_add_f32 v[76:77], v[188:189], s[58:59] op_sel_hi:[0,1]
	v_pk_add_f32 v[78:79], v[188:189], s[60:61] op_sel_hi:[0,1]
	v_pk_add_f32 v[80:81], v[188:189], s[62:63] op_sel_hi:[0,1]
	v_and_b32_e32 v193, 0x7fffffff, v81
	v_and_b32_e32 v192, 0x7fffffff, v80
	v_and_b32_e32 v195, 0x7fffffff, v79
	v_and_b32_e32 v194, 0x7fffffff, v78
	v_and_b32_e32 v197, 0x7fffffff, v77
	v_and_b32_e32 v196, 0x7fffffff, v76
	v_and_b32_e32 v199, 0x7fffffff, v75
	v_and_b32_e32 v198, 0x7fffffff, v74
	v_and_b32_e32 v73, 0x7fffffff, v73
	v_and_b32_e32 v72, 0x7fffffff, v72
	v_and_b32_e32 v71, 0x7fffffff, v71
	v_and_b32_e32 v70, 0x7fffffff, v70
	v_and_b32_e32 v69, 0x7fffffff, v69
	v_and_b32_e32 v68, 0x7fffffff, v68
	v_and_b32_e32 v67, 0x7fffffff, v67
	v_and_b32_e32 v66, 0x7fffffff, v66
	v_pk_fma_f32 v[80:81], v[164:165], v[66:67], v[96:97]
	v_pk_fma_f32 v[78:79], v[164:165], v[68:69], v[94:95]
	v_pk_fma_f32 v[76:77], v[164:165], v[70:71], v[92:93]
	v_pk_fma_f32 v[74:75], v[164:165], v[72:73], v[90:91]
	v_pk_fma_f32 v[72:73], v[164:165], v[198:199], v[88:89]
	v_pk_fma_f32 v[70:71], v[164:165], v[196:197], v[86:87]
	v_pk_fma_f32 v[68:69], v[164:165], v[194:195], v[84:85]
	v_pk_fma_f32 v[66:67], v[168:169], v[192:193], v[82:83]
	s_mov_b64 vcc, 0
